# v119 variant: masked-loop LDS-DMA issued right after the K-fragment ds_read burst instead of before it; placement-matched
# speedup vs baseline: 1.0135x; 1.0007x over previous
; #define ATT_LAS __attribute__((address_space(3)))
; __device__ __forceinline__ void attn_unit(int uv, const float* sink_l, const bf16_t* P, bf16_t* Y, ATT_LAS unsigned char* lds, const float* rpb_l, const float* qn_l, const float* kn_l) {
;     ...
;         for (int t = 0; t < nlat; ++t) {
;             const int cur = t & 1, tl = a.t_lo + t;
;             if (t + 1 < nlat) { const size_t ro = (size_t)ATT_TROW(t + 5) * PITCH; kreg = *(const u32x4*)(kg + ro); vreg = *(const u32x4*)(vg + ro); }
;             bool need;
;             if (a.mode == 1) need = (tl * 64 + 63 >= qw - 128) && (tl * 64 <= qw + 31 + 128);
;             else { const int rs = clampi(qr - 4, 0, 120); need = (tl >= rs) && (tl < rs + 8); }
;             if (need) {
;                 const ATT_LAS unsigned char* Kb = ATT_KBUF(cur); const ATT_LAS unsigned char* Vb = ATT_VBUF(cur);
.LBB0_657:
	s_lshl_b32 s86, s32, 13
	s_cmp_eq_u32 s32, 2
	s_cselect_b32 s87, 0x6000, s86
	v_add_u32_e32 v40, s86, v221
	v_add_u32_e32 v242, s87, v125
	ds_read_b128 v[128:131], v40
	ds_read_b128 v[132:135], v40 offset:512
	ds_read_b128 v[136:139], v40 offset:2048
	ds_read_b128 v[140:143], v40 offset:2560
	ds_read_b128 v[144:147], v40 offset:4096
	ds_read_b128 v[148:151], v40 offset:4608
	ds_read_b128 v[152:155], v40 offset:6144
	ds_read_b128 v[156:159], v40 offset:6656
	s_cmp_lg_u64 s[82:83], 0
	s_cbranch_scc0 .Lmkd_head
	s_add_i32 s80, s32, 2
	s_cmp_ge_u32 s80, 3
	s_cselect_b32 s81, 3, 0
	s_sub_i32 s80, s80, s81
	s_lshl_b32 s81, s80, 13
	s_add_i32 s96, s81, 0x6000
	s_cmp_eq_u32 s80, 2
	s_cselect_b32 s80, 0xc000, s96
	s_add_i32 s81, s81, s100
	s_mov_b32 m0, s81
	s_nop 0
	global_load_lds_dwordx4 v[112:113], off
	s_add_i32 s80, s80, s100
	s_mov_b32 m0, s80
	s_nop 0
	global_load_lds_dwordx4 v[114:115], off
	v_lshl_add_u64 v[112:113], v[112:113], 0, s[98:99]
	v_lshl_add_u64 v[114:115], v[114:115], 0, s[98:99]
.Lmkd_head:
	s_cmp_lt_i32 s7, 4
	s_cbranch_scc0 .Lmk_lat

; #define ATT_LAS __attribute__((address_space(3)))
; __device__ __forceinline__ void attn_unit(int uv, const float* sink_l, const bf16_t* P, bf16_t* Y, ATT_LAS unsigned char* lds, const float* rpb_l, const float* qn_l, const float* kn_l) {
;     ...
;         for (int t = 0; t < nlat; ++t) {
;             const int cur = t & 1, tl = a.t_lo + t;
;             if (t + 1 < nlat) { const size_t ro = (size_t)ATT_TROW(t + 5) * PITCH; kreg = *(const u32x4*)(kg + ro); vreg = *(const u32x4*)(vg + ro); }
;             bool need;
;             if (a.mode == 1) need = (tl * 64 + 63 >= qw - 128) && (tl * 64 <= qw + 31 + 128);
;             else { const int rs = clampi(qr - 4, 0, 120); need = (tl >= rs) && (tl < rs + 8); }
;             if (need) {
;     ...
;             if (t + 1 < nlat) { *(ATT_LAS u32x4*)(ATT_KBUF(cur ^ 1) + koff) = kreg; *(ATT_LAS u32x4*)(ATT_VBUF(cur ^ 1) + voff) = vreg; }
.Lmk_skip:
	s_cmp_lg_u64 s[82:83], 0
	s_cbranch_scc0 .Lmkd_skip
	s_add_i32 s80, s32, 2
	s_cmp_ge_u32 s80, 3
	s_cselect_b32 s81, 3, 0
	s_sub_i32 s80, s80, s81
	s_lshl_b32 s81, s80, 13
	s_add_i32 s96, s81, 0x6000
	s_cmp_eq_u32 s80, 2
	s_cselect_b32 s80, 0xc000, s96
	s_add_i32 s81, s81, s100
	s_mov_b32 m0, s81
	s_nop 0
	global_load_lds_dwordx4 v[112:113], off
	s_add_i32 s80, s80, s100
	s_mov_b32 m0, s80
	s_nop 0
	global_load_lds_dwordx4 v[114:115], off
	v_lshl_add_u64 v[112:113], v[112:113], 0, s[98:99]
	v_lshl_add_u64 v[114:115], v[114:115], 0, s[98:99]

; __device__ __forceinline__ unsigned xb_add(unsigned* p, unsigned v) { return __hip_atomic_fetch_add(p, v, __ATOMIC_RELAXED, __HIP_MEMORY_SCOPE_AGENT); }
; __device__ __forceinline__ void xcd_barrier(const XcdBarrier& b) {
;     asm volatile("s_waitcnt vmcnt(0)" ::: "memory");
;     __syncthreads();
;     if (threadIdx.x == 0) {
;         unsigned* bar = b.bar;
;         __builtin_amdgcn_s_waitcnt(0);
;         unsigned nloc = b.st[0], nx = b.st[1];
;         if (nloc == 0u) { xcd_barrier_complete(bar, b.x, nloc, nx); b.st[0] = nloc; b.st[1] = nx; }
;         const unsigned old = xb_add(&bar[XB_XSUB(b.x)], 1u);
.LBB0_699:
	s_lshl_b32 s2, s93, 6
	s_add_i32 s2, s2, s27
	s_add_i32 s2, s2, 64
	v_mad_i64_i32 v[32:33], s[2:3], s2, v215, v[198:199]
	global_load_dwordx4 v[120:123], v[32:33], off
	s_andn2_b64 vcc, exec, s[0:1]
	s_cbranch_vccz .LBB0_622
	s_branch .LBB0_623
	s_nop 0
	s_nop 0
	s_nop 0
	s_nop 0
	s_nop 0
	s_nop 0
	s_nop 0
	s_nop 0
	s_nop 0
	s_nop 0
	s_nop 0
	s_nop 0
	s_nop 0
	s_nop 0
.LBB0_700:
	s_mov_b32 s0, 0
	s_add_i32 s21, s0, 0
	s_add_i32 s0, s21, 0x200b8
	v_mov_b32_e32 v0, s0
	ds_read_b64 v[0:1], v0
	s_getreg_b32 s2, hwreg(HW_REG_XCC_ID, 0, 4)
	s_waitcnt vmcnt(0)
	s_waitcnt lgkmcnt(0)
	s_barrier
	v_readfirstlane_b32 s5, v1
	v_readfirstlane_b32 s4, v0
	s_mov_b64 s[0:1], exec
	v_readlane_b32 s6, v255, 0
	v_readlane_b32 s7, v255, 1
	s_and_b64 s[6:7], s[0:1], s[6:7]
	v_readlane_b32 s79, v255, 4
	s_mov_b32 s80, 0x20000
	s_movk_i32 s81, 0x2000
	s_movk_i32 s83, 0x1000
	s_mov_b32 s84, 0x400000
	s_mov_b32 s85, 0x800000
	s_mov_b32 s86, 0xc00000
	s_mov_b32 s87, 0xf800000
	s_mov_b32 s95, 0x40000
	s_mov_b32 s91, 0x60000
	s_movk_i32 s74, 0x16c
	s_mov_b32 s92, 0x10000
	s_movk_i32 s93, 0xffbf
	s_mov_b32 s94, 0x30000
	s_mov_b32 s76, 0x80000
	s_mov_b32 s77, 0x90000
	s_mov_b64 exec, s[6:7]
	s_cbranch_execz .LBB0_752
	s_add_i32 s22, s21, 0x20100
	v_mov_b32_e32 v0, s22
	s_add_i32 s21, s21, 0x20104
	s_waitcnt vmcnt(0) expcnt(0) lgkmcnt(0)
	ds_read_b32 v2, v0
	v_mov_b32_e32 v0, s21
	ds_read_b32 v0, v0
	s_and_b32 s20, s2, 15
	s_add_u32 s2, s4, 0x200
	s_waitcnt lgkmcnt(1)
	v_cmp_ne_u32_e32 vcc, 0, v2
	s_addc_u32 s3, s5, 0
	s_cbranch_vccnz .LBB0_716
	s_add_u32 s6, s4, 0x1000
	s_addc_u32 s7, s5, 0
	s_add_u32 s8, s4, 0x1100
	s_addc_u32 s9, s5, 0
	s_add_u32 s10, s4, 0x1200
	s_addc_u32 s11, s5, 0
	s_add_u32 s12, s4, 0x1300
	s_addc_u32 s13, s5, 0
	s_mov_b32 s23, 1
	s_branch .LBB0_704
